# GEMM job prologue: second k-tile LDS-DMA loads issued before the first-tile wait and barrier (vmcnt 2 -> 8)
# baseline (speedup 1.0000x reference)
; #define PG8_STAGE(bufoff, gbase, voff) do { _Pragma("unroll") for (int _i = 0; _i < 2; ++_i) \
;     __builtin_amdgcn_global_load_lds((const unsigned*)((const char*)(gbase) + (voff)[_i]), (PG8_LAS unsigned*)(lds + (bufoff) + ldsw + _i * 8192), 16, 0, 0); } while (0)
; #define PG8_WAIT_V(n) asm volatile("s_waitcnt vmcnt(" #n ")" ::: "memory")
; #define PG8_BAR __builtin_amdgcn_s_barrier()
; template <class Epi>
; DEV void gemm_phase(PG8_LAS unsigned char* lds, const Gemm g, const StaticOrder& S, const Epi& E) {
;     ...
;   PG8_STAGE(PG8_SB(0, 0), cB, voffB); PG8_STAGE(PG8_SB(0, 1), cB + hstepB, voffB); PG8_STAGE(PG8_SA(0, 0), cA, voffA); PG8_STAGE(PG8_SA(0, 1), cA + hstepA, voffA);
;   if (wr == 1) PG8_BAR;
;   PG8_WAIT_V(2); PG8_BAR;
;   PG8_STAGE(PG8_SB(1, 0), cB + kstep, voffB); PG8_STAGE(PG8_SA(1, 0), cA + kstepA, voffA); PG8_STAGE(PG8_SB(1, 1), cB + hstepB + kstep, voffB);
;   PG8_WAIT_V(6); PG8_BAR;
.LBB0_542:
	s_and_b32 s38, s1, 3
	s_lshr_b32 s36, s40, 6
	s_lshl_b64 s[8:9], s[34:35], 3
	s_and_b64 s[12:13], s[12:13], exec
	s_cselect_b32 s35, 0, s9
	s_cselect_b32 s34, 0x80, s8
	s_lshl_b32 s37, s0, 6
	s_lshl_b32 s7, s0, 13
	s_lshl_b32 s11, s38, 12
	s_add_u32 s88, s42, 0x5dcd000
	s_addc_u32 s89, s43, 0
	s_add_i32 s0, s2, 0x18000
	s_add_i32 s1, s2, 0x1a000
	v_lshl_add_u64 v[0:1], v[0:1], 0, s[96:97]
	s_mov_b32 m0, s0
	s_add_u32 s8, s44, s34
	v_mov_b32_e32 v183, v41
	global_load_lds_dwordx4 v[0:1], off
	v_lshl_add_u64 v[0:1], v[2:3], 0, s[96:97]
	s_mov_b32 m0, s1
	s_addc_u32 s9, s45, s35
	s_add_i32 s16, s2, 0x8000
	v_mov_b32_e32 v179, v41
	global_load_lds_dwordx4 v[0:1], off
	v_lshl_add_u64 v[0:1], s[8:9], 0, v[182:183]
	s_mov_b32 m0, s16
	s_add_i32 s17, s2, 0xa000
	global_load_lds_dwordx4 v[0:1], off
	v_lshl_add_u64 v[0:1], s[8:9], 0, v[178:179]
	s_mov_b32 m0, s17
	s_add_i32 s76, s2, 0x1c000
	global_load_lds_dwordx4 v[0:1], off
	v_lshl_add_u64 v[0:1], v[4:5], 0, s[96:97]
	s_mov_b32 m0, s76
	s_add_i32 s77, s2, 0x1e000
	global_load_lds_dwordx4 v[0:1], off
	v_lshl_add_u64 v[0:1], v[6:7], 0, s[96:97]
	s_mov_b32 m0, s77
	s_add_i32 s53, s36, -2
	global_load_lds_dwordx4 v[0:1], off
	s_waitcnt vmcnt(8)
	s_barrier
	v_bfe_u32 v0, v8, 4, 2
	v_and_b32_e32 v222, 15, v8
	v_lshlrev_b32_e32 v2, 4, v0
	v_lshlrev_b32_e32 v3, 2, v8
	s_cmpk_lt_u32 s6, 0x100
	v_lshl_or_b32 v2, v222, 6, v2
	v_and_b32_e32 v3, 32, v3
	s_cselect_b64 s[12:13], -1, 0
	s_cmp_gt_u32 s38, 1
	v_bitop3_b32 v223, v2, s7, v3 bitop3:0xde
	v_writelane_b32 v255, s38, 28
	s_cselect_b64 s[6:7], -1, 0
	v_writelane_b32 v255, s6, 29
	s_and_b32 s68, s90, 7
	s_lshl_b32 s69, s50, 3
	v_writelane_b32 v255, s7, 30
	s_lshr_b32 s6, s90, 3
	v_writelane_b32 v255, s6, 31
	s_add_i32 s6, s6, 1
	v_writelane_b32 v255, s6, 32
	s_add_i32 s6, s10, -1
	s_cmp_gt_u32 s6, 2
	v_lshlrev_b32_e32 v1, 3, v0
	s_cselect_b64 s[6:7], -1, 0
	v_lshl_or_b32 v225, s38, 5, v1
	v_cmp_eq_u32_e64 s[38:39], 0, v0
	v_writelane_b32 v255, s6, 33
	v_cvt_f32_u32_e32 v0, s69
	s_add_i32 s40, s10, -6
	v_writelane_b32 v255, s7, 34
	s_lshl_b64 s[6:7], s[40:41], 4
	v_readlane_b32 s8, v255, 6
	v_readlane_b32 s9, v255, 7
	s_add_u32 s6, s8, s6
	s_addc_u32 s7, s9, s7
	v_rcp_iflag_f32_e32 v0, v0
	v_writelane_b32 v255, s6, 35
	s_cmp_lg_u64 s[8:9], 0
	v_and_b32_e32 v1, 16, v8
	v_writelane_b32 v255, s7, 36
	s_cselect_b64 s[6:7], -1, 0
	s_and_b64 s[4:5], s[4:5], s[6:7]
	v_writelane_b32 v255, s4, 37
	s_waitcnt lgkmcnt(0)
	s_cmp_lg_u64 s[86:87], 0
	v_mul_f32_e32 v0, 0x4f7ffffe, v0
	v_writelane_b32 v255, s5, 38
	s_cselect_b64 s[4:5], -1, 0
	v_cvt_u32_f32_e32 v0, v0
	v_writelane_b32 v255, s4, 39
	v_cmp_eq_u32_e32 vcc, 0, v1
	v_mov_b32_e32 v1, 0x3c23d70a
	v_writelane_b32 v255, s5, 40
	s_add_u32 s4, s46, 0xf8000000
	v_writelane_b32 v255, s4, 41
	s_addc_u32 s4, s47, -1
	v_writelane_b32 v255, s4, 42
	s_sub_i32 s4, 0, s69
	v_readfirstlane_b32 s5, v0
	s_mul_i32 s4, s4, s5
	s_mul_hi_u32 s4, s5, s4
	v_bitop3_b32 v224, v2, s11, v3 bitop3:0xde
	v_cndmask_b32_e64 v226, v1, 1.0, vcc
	v_mov_b32_e32 v1, 0x3b4f3e37
	v_mov_b32_e32 v2, 0x3ea1e89b
	s_add_i32 s4, s5, s4
	s_lshl_b64 s[6:7], s[34:35], 1
	s_waitcnt vmcnt(6)
	v_cndmask_b32_e32 v227, v1, v2, vcc
	v_mov_b32_e32 v1, 0x3a83126f
	v_mov_b32_e32 v2, 0x3dcccccd
	v_writelane_b32 v255, s4, 43
	s_add_u32 s4, s34, s22
	v_cndmask_b32_e32 v228, v1, v2, vcc
	v_mov_b32_e32 v1, 0x39a5cb5f
	v_mov_b32_e32 v2, 0x3d0186e2
	v_lshlrev_b32_e32 v40, 1, v225
	s_addc_u32 s5, s35, s23
	s_mov_b32 s52, 0
	v_subrev_u32_e32 v186, 64, v225
	v_mov_b32_e32 v187, v41
	v_cndmask_b32_e32 v229, v1, v2, vcc
	v_or_b32_e32 v230, 16, v222
	v_or_b32_e32 v231, 32, v222
	v_or_b32_e32 v232, 48, v222
	s_mov_b32 s91, s41
	v_lshl_add_u64 v[188:189], s[62:63], 0, v[40:41]
	s_mov_b32 s81, s41
	v_lshl_add_u64 v[190:191], s[4:5], 0, v[182:183]
	v_lshl_add_u64 v[192:193], s[4:5], 0, v[178:179]
	s_add_i32 s5, s2, 0xe000
	s_barrier
	s_branch .LBB0_545
